# stick-breaking attention: priority raise kept only on the pure-MFMA burst; the VALU-heavy interleaved segments run at base priority
# speedup vs baseline: 1.0007x; 1.0007x over previous
.LBB0_41:
	s_add_i32 s0, s42, -1
	v_cmp_le_i32_e32 vcc, s2, v198
	s_and_b32 s45, s0, 1
	s_cbranch_vccnz .LBB0_44
	v_cmp_gt_f32_e32 vcc, s58, v172
	s_cmp_eq_u64 vcc, exec
	s_cbranch_scc1 .LBB0_44
	s_mul_i32 s0, s45, 0x8c00
	s_add_i32 s0, s0, 0
	v_add_u32_e32 v0, s0, v189
	v_add_u32_e32 v173, v0, v188
	ds_read_b128 v[174:177], v173 offset:8704
	ds_read_b128 v[200:203], v173 offset:8736
	ds_read_b128 v[204:207], v173 offset:8768
	ds_read_b128 v[208:211], v173 offset:8800
	ds_read_b128 v[212:215], v173 offset:8832
	ds_read_b128 v[216:219], v173 offset:8864
	ds_read_b128 v[220:223], v173 offset:8896
	ds_read_b128 v[224:227], v173 offset:8928
	ds_read_b128 v[66:69], v173
	ds_read_b128 v[232:235], v173 offset:32
	s_setprio 1
	s_waitcnt lgkmcnt(9)
	v_mfma_f32_32x32x16_bf16 v[82:97], v[174:177], v[98:101], 0
	s_waitcnt lgkmcnt(8)
	v_mfma_f32_32x32x16_bf16 v[82:97], v[200:203], v[102:105], v[82:97]
	s_waitcnt lgkmcnt(7)
	v_mfma_f32_32x32x16_bf16 v[82:97], v[204:207], v[106:109], v[82:97]
	s_waitcnt lgkmcnt(6)
	v_mfma_f32_32x32x16_bf16 v[82:97], v[208:211], v[110:113], v[82:97]
	s_waitcnt lgkmcnt(5)
	v_mfma_f32_32x32x16_bf16 v[82:97], v[212:215], v[114:117], v[82:97]
	s_waitcnt lgkmcnt(4)
	v_mfma_f32_32x32x16_bf16 v[82:97], v[216:219], v[118:121], v[82:97]
	ds_read_b128 v[216:219], v173 offset:64
	s_waitcnt lgkmcnt(4)
	v_mfma_f32_32x32x16_bf16 v[82:97], v[220:223], v[122:125], v[82:97]
	ds_read_b128 v[220:223], v173 offset:96
	s_waitcnt lgkmcnt(4)
	v_mfma_f32_32x32x16_bf16 v[82:97], v[224:227], v[126:129], v[82:97]
	ds_read_b128 v[224:227], v173 offset:128
	s_setprio 0
	s_waitcnt lgkmcnt(4)
	v_mfma_f32_32x32x16_bf16 v[66:81], v[66:69], v[98:101], 0
	s_waitcnt lgkmcnt(3)
	v_mfma_f32_32x32x16_bf16 v[66:81], v[232:235], v[102:105], v[66:81]
	ds_read_b128 v[232:235], v173 offset:160
	s_nop 3
	v_mov_b32_e32 v236, 1.0
	v_cmp_gt_i32_e32 vcc, 28, v159
	s_cmp_eq_u64 vcc, 0
	s_cbranch_scc1 .Lstk_nm1
	v_cmp_lt_i32_e64 s[0:1], 0, v159
	v_cmp_lt_i32_e64 s[8:9], 1, v159
	v_cmp_lt_i32_e64 s[10:11], 2, v159
	v_cmp_lt_i32_e64 s[12:13], 3, v159
	v_cndmask_b32_e64 v82, v231, v82, s[0:1]
	v_cndmask_b32_e64 v83, v231, v83, s[8:9]
	v_cndmask_b32_e64 v84, v231, v84, s[10:11]
	v_cndmask_b32_e64 v85, v231, v85, s[12:13]
	v_cmp_lt_i32_e64 s[0:1], 8, v159
	v_cmp_lt_i32_e64 s[8:9], 9, v159
	v_cmp_lt_i32_e64 s[10:11], 10, v159
	v_cmp_lt_i32_e64 s[12:13], 11, v159
	v_cndmask_b32_e64 v86, v231, v86, s[0:1]
	v_cndmask_b32_e64 v87, v231, v87, s[8:9]
	v_cndmask_b32_e64 v88, v231, v88, s[10:11]
	v_cndmask_b32_e64 v89, v231, v89, s[12:13]
	v_cmp_lt_i32_e64 s[0:1], 16, v159
	v_cmp_lt_i32_e64 s[8:9], 17, v159
	v_cmp_lt_i32_e64 s[10:11], 18, v159
	v_cmp_lt_i32_e64 s[12:13], 19, v159
	v_cndmask_b32_e64 v90, v231, v90, s[0:1]
	v_cndmask_b32_e64 v91, v231, v91, s[8:9]
	v_cndmask_b32_e64 v92, v231, v92, s[10:11]
	v_cndmask_b32_e64 v93, v231, v93, s[12:13]
	v_cmp_lt_i32_e64 s[0:1], 24, v159
	v_cmp_lt_i32_e64 s[8:9], 25, v159
	v_cmp_lt_i32_e64 s[10:11], 26, v159
	v_cmp_lt_i32_e64 s[12:13], 27, v159
	v_cndmask_b32_e64 v94, v231, v94, s[0:1]
	v_cndmask_b32_e64 v95, v231, v95, s[8:9]
	v_cndmask_b32_e64 v96, v231, v96, s[10:11]
	v_cndmask_b32_e64 v97, v231, v97, s[12:13]
.Lstk_nm1:
	s_waitcnt lgkmcnt(3)
	v_mfma_f32_32x32x16_bf16 v[66:81], v[216:219], v[106:109], v[66:81]
	ds_read_b128 v[216:219], v173 offset:192
	v_exp_f32_e64 v200, -|v82|
	v_exp_f32_e64 v201, -|v83|
	v_exp_f32_e64 v202, -|v84|
	v_exp_f32_e64 v203, -|v85|
	v_pk_add_f32 v[200:201], v[200:201], v[236:237] op_sel_hi:[1,0]
	v_max_i32_e32 v174, 0, v82
	v_max_i32_e32 v175, 0, v83
	v_log_f32_e32 v200, v200
	v_log_f32_e32 v201, v201
	v_exp_f32_e64 v204, -|v86|
	v_exp_f32_e64 v205, -|v87|
	v_pk_add_f32 v[202:203], v[202:203], v[236:237] op_sel_hi:[1,0]
	s_waitcnt lgkmcnt(3)
	v_mfma_f32_32x32x16_bf16 v[66:81], v[220:223], v[110:113], v[66:81]
	ds_read_b128 v[220:223], v173 offset:224
	v_max_i32_e32 v176, 0, v84
	v_max_i32_e32 v177, 0, v85
	v_log_f32_e32 v202, v202
	v_log_f32_e32 v203, v203
	v_pk_add_f32 v[200:201], v[200:201], v[174:175]
	v_pk_add_f32 v[82:83], v[82:83], v[200:201] neg_lo:[0,1] neg_hi:[0,1]
	v_exp_f32_e64 v206, -|v88|
	v_exp_f32_e64 v207, -|v89|
	v_pk_add_f32 v[204:205], v[204:205], v[236:237] op_sel_hi:[1,0]
	v_max_i32_e32 v174, 0, v86
	v_max_i32_e32 v175, 0, v87
	v_log_f32_e32 v204, v204
	s_waitcnt lgkmcnt(3)
	v_mfma_f32_32x32x16_bf16 v[66:81], v[224:227], v[114:117], v[66:81]
	v_log_f32_e32 v205, v205
	v_pk_add_f32 v[202:203], v[202:203], v[176:177]
	v_pk_add_f32 v[84:85], v[84:85], v[202:203] neg_lo:[0,1] neg_hi:[0,1]
	v_exp_f32_e64 v208, -|v90|
	v_exp_f32_e64 v209, -|v91|
	v_pk_add_f32 v[206:207], v[206:207], v[236:237] op_sel_hi:[1,0]
	v_max_i32_e32 v176, 0, v88
	v_max_i32_e32 v177, 0, v89
	v_log_f32_e32 v206, v206
	v_log_f32_e32 v207, v207
	v_pk_add_f32 v[204:205], v[204:205], v[174:175]
	v_pk_add_f32 v[86:87], v[86:87], v[204:205] neg_lo:[0,1] neg_hi:[0,1]
	s_waitcnt lgkmcnt(2)
	v_mfma_f32_32x32x16_bf16 v[66:81], v[232:235], v[118:121], v[66:81]
	v_exp_f32_e64 v210, -|v92|
	v_exp_f32_e64 v211, -|v93|
	v_pk_add_f32 v[208:209], v[208:209], v[236:237] op_sel_hi:[1,0]
	v_max_i32_e32 v174, 0, v90
	v_max_i32_e32 v175, 0, v91
	v_log_f32_e32 v208, v208
	v_log_f32_e32 v209, v209
	v_pk_add_f32 v[206:207], v[206:207], v[176:177]
	v_pk_add_f32 v[88:89], v[88:89], v[206:207] neg_lo:[0,1] neg_hi:[0,1]
	v_exp_f32_e64 v212, -|v94|
	v_exp_f32_e64 v213, -|v95|
	v_pk_add_f32 v[210:211], v[210:211], v[236:237] op_sel_hi:[1,0]
	s_waitcnt lgkmcnt(1)
	v_mfma_f32_32x32x16_bf16 v[66:81], v[216:219], v[122:125], v[66:81]
	v_max_i32_e32 v176, 0, v92
	v_max_i32_e32 v177, 0, v93
	v_log_f32_e32 v210, v210
	v_log_f32_e32 v211, v211
	v_pk_add_f32 v[208:209], v[208:209], v[174:175]
	v_pk_add_f32 v[90:91], v[90:91], v[208:209] neg_lo:[0,1] neg_hi:[0,1]
	v_exp_f32_e64 v214, -|v96|
	v_exp_f32_e64 v215, -|v97|
	v_pk_add_f32 v[212:213], v[212:213], v[236:237] op_sel_hi:[1,0]
	v_max_i32_e32 v174, 0, v94
	v_max_i32_e32 v175, 0, v95
	v_log_f32_e32 v212, v212
	s_waitcnt lgkmcnt(0)
	v_mfma_f32_32x32x16_bf16 v[66:81], v[220:223], v[126:129], v[66:81]
	v_log_f32_e32 v213, v213
	v_pk_add_f32 v[210:211], v[210:211], v[176:177]
	v_pk_add_f32 v[92:93], v[92:93], v[210:211] neg_lo:[0,1] neg_hi:[0,1]
	v_pk_add_f32 v[214:215], v[214:215], v[236:237] op_sel_hi:[1,0]
	v_max_i32_e32 v176, 0, v96
	v_max_i32_e32 v177, 0, v97
	v_log_f32_e32 v214, v214
	v_log_f32_e32 v215, v215
	v_pk_add_f32 v[212:213], v[212:213], v[174:175]
	v_pk_add_f32 v[94:95], v[94:95], v[212:213] neg_lo:[0,1] neg_hi:[0,1]
	v_pk_add_f32 v[214:215], v[214:215], v[176:177]
	v_pk_add_f32 v[96:97], v[96:97], v[214:215] neg_lo:[0,1] neg_hi:[0,1]
	s_setprio 0
	v_cndmask_b32_e64 v173, 0, 1.0, s[4:5]
	v_pk_add_f32 v[174:175], v[200:201], v[202:203]
	v_add_f32_e32 v216, v174, v175
	v_mov_b32_e32 v220, v216
	v_pk_add_f32 v[176:177], v[204:205], v[206:207]
	v_add_f32_e32 v217, v176, v177
	v_mov_b32_e32 v221, v217
	v_pk_add_f32 v[174:175], v[208:209], v[210:211]
	v_add_f32_e32 v218, v174, v175
	v_mov_b32_e32 v222, v218
	v_pk_add_f32 v[176:177], v[212:213], v[214:215]
	v_add_f32_e32 v219, v176, v177
	v_mov_b32_e32 v223, v219
	s_nop 1
	v_permlane32_swap_b32_e32 v216, v220
	v_permlane32_swap_b32_e32 v217, v221
	v_permlane32_swap_b32_e32 v218, v222
	v_permlane32_swap_b32_e32 v219, v223
	v_add_f32_e32 v216, v216, v220
	v_add_f32_e32 v217, v217, v221
	v_add_f32_e32 v218, v218, v222
	v_add_f32_e32 v219, v219, v223
	v_fma_f32 v233, -v223, v173, v172
	v_sub_f32_e32 v232, v233, v215
	v_sub_f32_e32 v229, v232, v214
	v_sub_f32_e32 v228, v229, v213
	v_pk_add_f32 v[96:97], v[96:97], v[232:233]
	v_pk_add_f32 v[94:95], v[94:95], v[228:229]
	v_exp_f32_e32 v96, v96
	v_exp_f32_e32 v97, v97
	v_exp_f32_e32 v94, v94
	v_exp_f32_e32 v95, v95
	v_sub_f32_e32 v227, v172, v219
	v_fma_f32 v177, -v222, v173, v227
	v_sub_f32_e32 v176, v177, v211
	v_sub_f32_e32 v235, v176, v210
	v_sub_f32_e32 v234, v235, v209
	v_pk_add_f32 v[92:93], v[92:93], v[176:177]
	v_pk_add_f32 v[90:91], v[90:91], v[234:235]
	v_exp_f32_e32 v92, v92
	v_exp_f32_e32 v93, v93
	v_exp_f32_e32 v90, v90
	v_exp_f32_e32 v91, v91
	v_sub_f32_e32 v226, v227, v218
	v_fma_f32 v233, -v221, v173, v226
	v_sub_f32_e32 v232, v233, v207
	v_sub_f32_e32 v229, v232, v206
	v_sub_f32_e32 v228, v229, v205
	v_pk_add_f32 v[88:89], v[88:89], v[232:233]
	v_pk_add_f32 v[86:87], v[86:87], v[228:229]
	v_exp_f32_e32 v88, v88
	v_exp_f32_e32 v89, v89
	v_exp_f32_e32 v86, v86
	v_exp_f32_e32 v87, v87
	v_sub_f32_e32 v227, v226, v217
	v_fma_f32 v177, -v220, v173, v227
	v_sub_f32_e32 v182, v227, v216
	v_sub_f32_e32 v176, v177, v203
	v_sub_f32_e32 v235, v176, v202
	v_sub_f32_e32 v234, v235, v201
	v_pk_add_f32 v[84:85], v[84:85], v[176:177]
	v_pk_add_f32 v[82:83], v[82:83], v[234:235]
	v_exp_f32_e32 v84, v84
	v_exp_f32_e32 v85, v85
	v_exp_f32_e32 v82, v82
	v_exp_f32_e32 v83, v83
	v_add_u32_e32 v0, v0, v191
	v_cvt_pk_bf16_f32 v82, v82, v83
	v_cvt_pk_bf16_f32 v83, v84, v85
	v_cvt_pk_bf16_f32 v84, v86, v87
	v_cvt_pk_bf16_f32 v85, v88, v89
	v_cvt_pk_bf16_f32 v86, v90, v91
	v_cvt_pk_bf16_f32 v87, v92, v93
	v_cvt_pk_bf16_f32 v88, v94, v95
	v_cvt_pk_bf16_f32 v89, v96, v97
	ds_read_b128 v[90:93], v0 offset:17472
	ds_read_b128 v[94:97], v0 offset:22080
	s_waitcnt lgkmcnt(1)
	v_mfma_f32_32x32x16_bf16 v[50:65], v[90:93], v[82:85], v[50:65]
	ds_read_b128 v[90:93], v0 offset:26688
	s_waitcnt lgkmcnt(1)
	v_mfma_f32_32x32x16_bf16 v[34:49], v[94:97], v[82:85], v[34:49]
	ds_read_b128 v[94:97], v0 offset:31296
	v_add_u32_e32 v199, 32, v159
	v_cmp_gt_i32_e32 vcc, 28, v199
	s_cmp_eq_u64 vcc, 0
	s_cbranch_scc1 .Lstk_nm0
	v_cmp_lt_i32_e64 s[0:1], 0, v199
	v_cmp_lt_i32_e64 s[8:9], 1, v199
	v_cmp_lt_i32_e64 s[10:11], 2, v199
	v_cmp_lt_i32_e64 s[12:13], 3, v199
	v_cndmask_b32_e64 v66, v231, v66, s[0:1]
	v_cndmask_b32_e64 v67, v231, v67, s[8:9]
	v_cndmask_b32_e64 v68, v231, v68, s[10:11]
	v_cndmask_b32_e64 v69, v231, v69, s[12:13]
	v_cmp_lt_i32_e64 s[0:1], 8, v199
	v_cmp_lt_i32_e64 s[8:9], 9, v199
	v_cmp_lt_i32_e64 s[10:11], 10, v199
	v_cmp_lt_i32_e64 s[12:13], 11, v199
	v_cndmask_b32_e64 v70, v231, v70, s[0:1]
	v_cndmask_b32_e64 v71, v231, v71, s[8:9]
	v_cndmask_b32_e64 v72, v231, v72, s[10:11]
	v_cndmask_b32_e64 v73, v231, v73, s[12:13]
	v_cmp_lt_i32_e64 s[0:1], 16, v199
	v_cmp_lt_i32_e64 s[8:9], 17, v199
	v_cmp_lt_i32_e64 s[10:11], 18, v199
	v_cmp_lt_i32_e64 s[12:13], 19, v199
	v_cndmask_b32_e64 v74, v231, v74, s[0:1]
	v_cndmask_b32_e64 v75, v231, v75, s[8:9]
	v_cndmask_b32_e64 v76, v231, v76, s[10:11]
	v_cndmask_b32_e64 v77, v231, v77, s[12:13]
	v_cmp_lt_i32_e64 s[0:1], 24, v199
	v_cmp_lt_i32_e64 s[8:9], 25, v199
	v_cmp_lt_i32_e64 s[10:11], 26, v199
	v_cmp_lt_i32_e64 s[12:13], 27, v199
	v_cndmask_b32_e64 v78, v231, v78, s[0:1]
	v_cndmask_b32_e64 v79, v231, v79, s[8:9]
	v_cndmask_b32_e64 v80, v231, v80, s[10:11]
	v_cndmask_b32_e64 v81, v231, v81, s[12:13]
